# ATTN: mask-word load ahead of the K/V DMA pair (head wait vmcnt(2)), interleaved far-tile schedule; grid barriers 2..10: single cross-XCC counter polled by every WG
# speedup vs baseline: 1.0056x; 1.0056x over previous
_Z4mega4Args:
	s_load_dword s3, s[0:1], 0xd0
	s_mov_b32 s98, 1
	s_add_u32 s4, s0, 0xd0
	s_mov_b32 s86, s2
	s_addc_u32 s5, s1, 0
	v_readfirstlane_b32 s44, v0
	s_waitcnt lgkmcnt(0)
	s_and_b32 s2, s3, 7
	v_writelane_b32 v238, s4, 0
	s_cmp_lg_u32 s2, 0
	s_mov_b32 s92, s86
	v_writelane_b32 v238, s5, 1
	s_cbranch_scc1 .LBB0_2
	s_ashr_i32 s4, s86, 31
	s_lshr_b32 s4, s4, 29
	s_add_i32 s4, s86, s4
	s_and_b32 s5, s4, -8
	s_ashr_i32 s2, s3, 3
	s_sub_i32 s5, s86, s5
	s_mul_i32 s2, s2, s5
	s_ashr_i32 s4, s4, 3
	s_add_i32 s92, s2, s4

.LBB0_510:
	s_cmp_gt_i32 s83, 2
	s_cselect_b64 s[0:1], -1, 0
	s_and_b64 s[4:5], s[10:11], s[0:1]
	v_readlane_b32 s38, v238, 36
	s_andn2_b64 vcc, exec, s[4:5]
	v_readlane_b32 s39, v238, 37
	s_mov_b32 s40, s92
	s_cbranch_vccnz .LBB0_564
	s_waitcnt vmcnt(0)
	s_waitcnt vmcnt(0)
	s_barrier
	s_and_saveexec_b64 s[4:5], s[38:39]
	s_cbranch_execz .LBB0_563
	s_add_u32 s98, s98, 1
	v_mov_b32_e32 v1, 0x25f20
	ds_read_b64 v[2:3], v1
	v_readlane_b32 s6, v238, 18
	v_readlane_b32 s7, v238, 19
	s_lshl_b32 s2, s87, 8
	s_addk_i32 s2, 0x1400
	v_mov_b32_e32 v1, s2
	v_mov_b32_e32 v5, 1
	s_nop 1
	global_atomic_add v1, v1, v5, s[6:7] sc0
	s_waitcnt vmcnt(0) lgkmcnt(0)
	v_readfirstlane_b32 s12, v1
	v_readfirstlane_b32 s9, v2
	v_readfirstlane_b32 s10, v3
	s_add_u32 s12, s12, 1
	s_mul_i32 s9, s9, s98
	s_mul_i32 s10, s10, s98
	v_mov_b32_e32 v1, 0x3400
	s_cmp_eq_u32 s12, s9
	s_cbranch_scc0 .Lfs0_spin
	buffer_wbl2 sc1
	s_waitcnt vmcnt(0)
	global_atomic_add v1, v5, s[6:7]
.Lfs0_spin:
	s_mov_b32 s11, 0
.Lfs0_loop:
	global_load_dword v2, v1, s[6:7] sc1
	s_add_u32 s11, s11, 1
	s_waitcnt vmcnt(0)
	v_readfirstlane_b32 s12, v2
	s_cmp_ge_u32 s12, s10
	s_cbranch_scc1 .Lfs0_done
	s_sleep 1
	s_cmp_lt_u32 s11, 0x100000
	s_cbranch_scc1 .Lfs0_loop
.Lfs0_done:
	buffer_inv sc1
	s_waitcnt vmcnt(0)

.LBB0_855:
	s_cmp_gt_i32 s83, 4
	s_cselect_b64 s[0:1], -1, 0
	s_and_b64 s[4:5], s[6:7], s[0:1]
	s_andn2_b64 vcc, exec, s[4:5]
	s_cbranch_vccnz .LBB0_909
	s_waitcnt vmcnt(0)
	s_waitcnt vmcnt(0) lgkmcnt(0)
	s_barrier
	s_and_saveexec_b64 s[4:5], s[38:39]
	s_cbranch_execz .LBB0_908
	s_add_u32 s98, s98, 1
	v_mov_b32_e32 v1, 0x25f20
	ds_read_b64 v[2:3], v1
	v_readlane_b32 s6, v238, 18
	v_readlane_b32 s7, v238, 19
	s_lshl_b32 s2, s87, 8
	s_addk_i32 s2, 0x1400
	v_mov_b32_e32 v1, s2
	v_mov_b32_e32 v5, 1
	s_nop 1
	global_atomic_add v1, v1, v5, s[6:7] sc0
	s_waitcnt vmcnt(0) lgkmcnt(0)
	v_readfirstlane_b32 s12, v1
	v_readfirstlane_b32 s9, v2
	v_readfirstlane_b32 s10, v3
	s_add_u32 s12, s12, 1
	s_mul_i32 s9, s9, s98
	s_mul_i32 s10, s10, s98
	v_mov_b32_e32 v1, 0x3400
	s_cmp_eq_u32 s12, s9
	s_cbranch_scc0 .Lfs1_spin
	buffer_wbl2 sc1
	s_waitcnt vmcnt(0)
	global_atomic_add v1, v5, s[6:7]

.LBB0_945:
	s_or_b64 exec, exec, s[4:5]
	s_ashr_i32 s4, s40, 5
	v_lshlrev_b32_e32 v1, 3, v176
	s_ashr_i32 s5, s4, 31
	v_and_b32_e32 v12, 24, v1
	v_lshlrev_b32_e32 v1, 2, v180
	s_and_b32 s2, s40, 3
	s_lshl_b64 s[8:9], s[4:5], 12
	v_and_or_b32 v2, v2, 3, v1
	s_lshl_b32 s16, s93, 5
	s_lshl_b32 s10, s6, 7
	v_lshlrev_b32_e32 v13, 6, v2
	v_mov_b32_e32 v2, 0
	s_add_u32 s6, s80, s10
	v_lshlrev_b32_e32 v4, 10, v179
	v_mov_b32_e32 v5, v2
	s_addc_u32 s7, s81, 0
	v_lshl_add_u64 v[4:5], s[6:7], 0, v[4:5]
	v_lshlrev_b32_e32 v6, 4, v180
	v_mov_b32_e32 v7, v2
	v_lshl_add_u64 v[4:5], v[4:5], 0, v[6:7]
	s_mov_b64 s[12:13], 0x2400000
	v_lshl_add_u64 v[114:115], v[4:5], 0, s[12:13]
	v_or_b32_e32 v4, s8, v176
	v_mov_b32_e32 v5, s9
	v_lshlrev_b64 v[8:9], 10, v[4:5]
	s_lshl_b32 s12, s93, 4
	v_lshrrev_b32_e32 v4, 2, v176
	v_and_or_b32 v4, s12, 48, v4
	v_or_b32_e32 v4, s8, v4
	v_lshlrev_b64 v[4:5], 10, v[4:5]
	s_lshl_b32 s4, s4, 6
	s_mov_b32 s11, 0
	v_lshl_add_u64 v[8:9], s[80:81], 0, v[8:9]
	v_lshl_add_u64 v[4:5], s[80:81], 0, v[4:5]
	s_ashr_i32 s5, s4, 31
	v_lshl_add_u64 v[8:9], v[8:9], 0, s[10:11]
	v_lshl_add_u64 v[4:5], v[4:5], 0, s[10:11]
	s_and_b32 s10, s12, 0x3fffffc0
	s_lshl_b64 s[4:5], s[4:5], 15
	v_lshl_add_u64 v[4:5], v[4:5], 0, s[10:11]
	v_lshlrev_b32_e32 v10, 1, v12
	v_mov_b32_e32 v11, v2
	s_add_u32 s4, s80, s4
	v_lshl_add_u64 v[4:5], v[4:5], 0, v[10:11]
	s_addc_u32 s5, s81, s5
	v_lshlrev_b32_e32 v10, 3, v179
	s_mov_b32 s13, s11
	v_lshl_add_u64 v[10:11], s[4:5], 0, v[10:11]
	s_mov_b64 s[4:5], 0x1db00000
	v_lshl_add_u64 v[8:9], v[8:9], 0, s[12:13]
	v_lshl_add_u64 v[120:121], v[10:11], 0, s[4:5]
	s_mov_b64 s[4:5], 0x4410000
	s_mov_b64 s[12:13], 0x6400000
	v_lshl_add_u64 v[122:123], v[8:9], 0, s[4:5]
	s_mov_b64 s[4:5], 0x6410000
	v_lshl_add_u64 v[118:119], v[4:5], 0, s[12:13]
	v_lshl_add_u64 v[124:125], v[4:5], 0, s[4:5]
	v_lshlrev_b32_e32 v4, 10, v180
	v_lshlrev_b32_e32 v5, 4, v179
	v_lshlrev_b32_e32 v3, 1, v0
	s_mov_b64 s[14:15], 0x4400000
	v_add3_u32 v140, 0, v4, v5
	s_lshl_b32 s4, s93, 12
	v_lshlrev_b32_e32 v4, 4, v176
	v_lshl_add_u64 v[116:117], v[8:9], 0, s[14:15]
	s_add_i32 s10, 0, 0x6000
	s_add_i32 s4, s4, 0
	v_lshrrev_b32_e32 v8, 3, v176
	v_and_b32_e32 v4, 0x70, v4
	v_mov_b32_e32 v5, v2
	v_and_or_b32 v3, v3, 32, v12
	v_lshl_add_u32 v7, v179, 1, s4
	v_add_u32_e32 v9, s4, v4
	v_lshl_add_u64 v[4:5], s[6:7], 0, v[4:5]
	s_mov_b64 s[4:5], 0x17b00000
	v_or_b32_e32 v10, 8, v8
	v_add3_u32 v141, v13, s10, v3
	v_lshlrev_b32_e32 v3, 2, v179
	s_lshl_b32 s20, s93, 10
	v_lshl_add_u64 v[126:127], v[4:5], 0, s[4:5]
	v_lshlrev_b32_e32 v4, 7, v8
	v_lshlrev_b32_e32 v128, 11, v8
	v_lshlrev_b32_e32 v11, 7, v10
	v_lshlrev_b32_e32 v130, 11, v10
	v_or_b32_e32 v10, 16, v8
	v_or_b32_e32 v8, 24, v8
	v_lshl_or_b32 v3, s93, 7, v3
	s_add_i32 s21, s20, 0
	v_lshlrev_b32_e32 v5, 9, v180
	v_lshlrev_b32_e32 v14, 7, v10
	v_lshlrev_b32_e32 v132, 11, v10
	v_lshlrev_b32_e32 v10, 7, v8
	v_sub_u32_e32 v3, v3, v6
	s_xor_b32 s17, s2, 7
	s_or_b32 s18, s2, 8
	s_xor_b32 s19, s2, 15
	s_add_i32 s22, s20, s10
	s_add_i32 s23, s21, 0x2000
	s_add_i32 s24, s21, 0x8000
	v_mov_b32_e32 v129, v2
	v_mov_b32_e32 v131, v2
	v_mov_b32_e32 v133, v2
	v_lshlrev_b32_e32 v134, 11, v8
	v_mov_b32_e32 v135, v2
	v_add_u32_e32 v142, 0, v3
	s_add_i32 s25, 0, 0x15000
	s_mov_b32 s4, 0x3f803f80
	v_add_u32_e32 v143, v7, v5
	v_add_u32_e32 v144, v9, v4
	v_add_u32_e32 v145, v9, v11
	v_add_u32_e32 v146, v9, v14
	v_add_u32_e32 v147, v9, v10
	s_mov_b32 s26, 0
	v_mov_b32_e32 v226, s4
	v_mov_b32_e32 v227, s4
	v_mov_b32_e32 v228, s4
	v_mov_b32_e32 v229, s4
	s_branch .LBB0_947

.LBB0_955:
	s_add_i32 s35, s15, -2
	s_lshl_b32 s5, s34, 13
	s_cmp_lt_u32 s15, s27
	s_cselect_b32 s10, s15, s29
	s_lshl_b64 s[6:7], s[10:11], 16
	s_waitcnt vmcnt(2)
	v_lshrrev_b32_e32 v3, v1, v138
	v_lshl_add_u64 v[6:7], v[116:117], 0, s[6:7]
	v_lshl_add_u64 v[8:9], v[118:119], 0, s[6:7]
	s_add_i32 s6, s5, 0xffffe000
	v_lshlrev_b32_e32 v3, 4, v3
	s_cmp_lg_u32 s34, 0
	v_and_b32_e32 v4, 0xf0f0f0f0, v3
	v_lshrrev_b32_e32 v3, v1, v139
	s_cselect_b32 s6, s6, 0x4000
	v_lshlrev_b32_e32 v3, 4, v3
	s_add_i32 s6, s6, 0
	v_and_b32_e32 v3, 0xf0f0f0f0, v3
	s_add_i32 s6, s20, s6
	s_add_i32 s36, s15, -1
	s_cmp_lt_u32 s35, 63
	s_cselect_b32 s36, s36, 63
	s_mov_b32 s37, 0
	s_lshl_b64 s[36:37], s[36:37], 15
	v_lshl_add_u64 v[150:151], v[136:137], 0, s[36:37]
	global_load_dwordx2 v[138:139], v[150:151], off
	s_waitcnt lgkmcnt(0)
	s_barrier
	s_add_i32 s7, s6, 0x6000
	s_mov_b32 m0, s6
	global_load_lds_dwordx4 v[6:7], off
	s_mov_b32 m0, s7
	global_load_lds_dwordx4 v[8:9], off
	s_cmp_gt_u32 s35, s28
	s_cbranch_scc1 .LBB0_954
	s_cmp_lt_u32 s33, s14
	s_cbranch_scc1 .Lattn_fast
	v_add_u32_sdwa v5, v4, s25 dst_sel:DWORD dst_unused:UNUSED_PAD src0_sel:BYTE_0 src1_sel:DWORD
	ds_read_b128 v[66:69], v5
	v_add_u32_sdwa v5, v3, s25 dst_sel:DWORD dst_unused:UNUSED_PAD src0_sel:BYTE_0 src1_sel:DWORD
	v_add_u32_e32 v14, s5, v140
	ds_read_b128 v[82:85], v5
	v_add_u32_sdwa v5, v4, s25 dst_sel:DWORD dst_unused:UNUSED_PAD src0_sel:BYTE_1 src1_sel:DWORD
	ds_read_b128 v[6:9], v14
	ds_read_b128 v[10:13], v14 offset:512
	ds_read_b128 v[70:73], v5
	v_add_u32_sdwa v5, v4, s25 dst_sel:DWORD dst_unused:UNUSED_PAD src0_sel:BYTE_2 src1_sel:DWORD
	v_add_u32_sdwa v4, v4, s25 dst_sel:DWORD dst_unused:UNUSED_PAD src0_sel:BYTE_3 src1_sel:DWORD
	ds_read_b128 v[78:81], v4
	v_add_u32_sdwa v4, v3, s25 dst_sel:DWORD dst_unused:UNUSED_PAD src0_sel:BYTE_1 src1_sel:DWORD
	ds_read_b128 v[86:89], v4
	v_add_u32_sdwa v4, v3, s25 dst_sel:DWORD dst_unused:UNUSED_PAD src0_sel:BYTE_2 src1_sel:DWORD
	v_add_u32_sdwa v3, v3, s25 dst_sel:DWORD dst_unused:UNUSED_PAD src0_sel:BYTE_3 src1_sel:DWORD
	ds_read_b128 v[74:77], v5
	ds_read_b128 v[90:93], v4
	ds_read_b128 v[94:97], v3
	s_waitcnt lgkmcnt(2)
	v_mfma_f32_32x32x16_bf16 v[66:81], v[6:9], v[110:113], v[66:81]
	s_cmp_lt_u32 s33, s14
	s_waitcnt lgkmcnt(0)
	v_mfma_f32_32x32x16_bf16 v[82:97], v[10:13], v[110:113], v[82:97]
	ds_read_b128 v[4:7], v14 offset:2048
	ds_read_b128 v[8:11], v14 offset:2560
	s_waitcnt lgkmcnt(1)
	v_mfma_f32_32x32x16_bf16 v[66:81], v[4:7], v[98:101], v[66:81]
	s_waitcnt lgkmcnt(0)
	v_mfma_f32_32x32x16_bf16 v[82:97], v[8:11], v[98:101], v[82:97]
	ds_read_b128 v[4:7], v14 offset:4096
	ds_read_b128 v[8:11], v14 offset:4608
	s_waitcnt lgkmcnt(1)
	v_mfma_f32_32x32x16_bf16 v[66:81], v[4:7], v[102:105], v[66:81]
	s_waitcnt lgkmcnt(0)
	v_mfma_f32_32x32x16_bf16 v[82:97], v[8:11], v[102:105], v[82:97]
	ds_read_b128 v[4:7], v14 offset:6144
	ds_read_b128 v[8:11], v14 offset:6656
	s_waitcnt lgkmcnt(1)
	v_mfma_f32_32x32x16_bf16 v[66:81], v[4:7], v[106:109], v[66:81]
	s_waitcnt lgkmcnt(0)
	v_mfma_f32_32x32x16_bf16 v[82:97], v[8:11], v[106:109], v[82:97]
	s_cbranch_scc1 .LBB0_953
	v_add_u32_e32 v3, s31, v148
	v_add_u32_e32 v4, 0x149fc, v3
	v_add_u32_e32 v6, 0x1497c, v3
	v_add_u32_e32 v8, 0x149f4, v3
	ds_read2_b32 v[4:5], v4 offset1:1
	ds_read2_b32 v[6:7], v6 offset1:1
	ds_read2_b32 v[8:9], v8 offset1:1
	v_add_u32_e32 v10, 0x14974, v3
	v_add_u32_e32 v12, 0x14954, v3
	s_waitcnt lgkmcnt(2)
	v_pk_add_f32 v[66:67], v[66:67], v[4:5] op_sel:[0,1] op_sel_hi:[1,0]
	s_waitcnt lgkmcnt(1)
	v_pk_add_f32 v[82:83], v[82:83], v[6:7] op_sel:[0,1] op_sel_hi:[1,0]
	s_waitcnt lgkmcnt(0)
	v_pk_add_f32 v[68:69], v[68:69], v[8:9] op_sel:[0,1] op_sel_hi:[1,0]
	v_add_u32_e32 v4, 0x149dc, v3
	v_add_u32_e32 v6, 0x1495c, v3
	v_add_u32_e32 v8, 0x149d4, v3
	ds_read2_b32 v[10:11], v10 offset1:1
	ds_read2_b32 v[4:5], v4 offset1:1
	ds_read2_b32 v[6:7], v6 offset1:1
	ds_read2_b32 v[8:9], v8 offset1:1
	ds_read2_b32 v[12:13], v12 offset1:1
	s_waitcnt lgkmcnt(3)
	v_pk_add_f32 v[70:71], v[70:71], v[4:5] op_sel:[0,1] op_sel_hi:[1,0]
	s_waitcnt lgkmcnt(2)
	v_pk_add_f32 v[86:87], v[86:87], v[6:7] op_sel:[0,1] op_sel_hi:[1,0]
	s_waitcnt lgkmcnt(1)
	v_pk_add_f32 v[72:73], v[72:73], v[8:9] op_sel:[0,1] op_sel_hi:[1,0]
	v_add_u32_e32 v4, 0x149bc, v3
	v_add_u32_e32 v6, 0x1493c, v3
	v_add_u32_e32 v8, 0x149b4, v3
	ds_read2_b32 v[4:5], v4 offset1:1
	ds_read2_b32 v[6:7], v6 offset1:1
	ds_read2_b32 v[8:9], v8 offset1:1
	v_pk_add_f32 v[84:85], v[84:85], v[10:11] op_sel:[0,1] op_sel_hi:[1,0]
	v_add_u32_e32 v10, 0x14934, v3
	s_waitcnt lgkmcnt(2)
	v_pk_add_f32 v[74:75], v[74:75], v[4:5] op_sel:[0,1] op_sel_hi:[1,0]
	s_waitcnt lgkmcnt(1)
	v_pk_add_f32 v[90:91], v[90:91], v[6:7] op_sel:[0,1] op_sel_hi:[1,0]
	s_waitcnt lgkmcnt(0)
	v_pk_add_f32 v[76:77], v[76:77], v[8:9] op_sel:[0,1] op_sel_hi:[1,0]
	v_add_u32_e32 v4, 0x1499c, v3
	v_add_u32_e32 v6, 0x1491c, v3
	v_add_u32_e32 v8, 0x14994, v3
	v_pk_add_f32 v[88:89], v[88:89], v[12:13] op_sel:[0,1] op_sel_hi:[1,0]
	ds_read2_b32 v[10:11], v10 offset1:1
	v_add_u32_e32 v3, 0x14914, v3
	ds_read2_b32 v[4:5], v4 offset1:1
	ds_read2_b32 v[6:7], v6 offset1:1
	ds_read2_b32 v[8:9], v8 offset1:1
	ds_read2_b32 v[12:13], v3 offset1:1
	s_waitcnt lgkmcnt(3)
	v_pk_add_f32 v[78:79], v[78:79], v[4:5] op_sel:[0,1] op_sel_hi:[1,0]
	v_pk_add_f32 v[92:93], v[92:93], v[10:11] op_sel:[0,1] op_sel_hi:[1,0]
	s_waitcnt lgkmcnt(2)
	v_pk_add_f32 v[94:95], v[94:95], v[6:7] op_sel:[0,1] op_sel_hi:[1,0]
	s_waitcnt lgkmcnt(1)
	v_pk_add_f32 v[80:81], v[80:81], v[8:9] op_sel:[0,1] op_sel_hi:[1,0]
	s_waitcnt lgkmcnt(0)
	v_pk_add_f32 v[96:97], v[96:97], v[12:13] op_sel:[0,1] op_sel_hi:[1,0]
	s_branch .LBB0_953
.Lattn_fast:
	v_add_u32_e32 v149, s5, v140
	v_add_u32_e32 v150, s5, v141
	v_add_u32_sdwa v230, v4, s25 dst_sel:DWORD dst_unused:UNUSED_PAD src0_sel:BYTE_0 src1_sel:DWORD
	v_add_u32_sdwa v231, v4, s25 dst_sel:DWORD dst_unused:UNUSED_PAD src0_sel:BYTE_1 src1_sel:DWORD
	v_add_u32_sdwa v232, v4, s25 dst_sel:DWORD dst_unused:UNUSED_PAD src0_sel:BYTE_2 src1_sel:DWORD
	v_add_u32_sdwa v233, v4, s25 dst_sel:DWORD dst_unused:UNUSED_PAD src0_sel:BYTE_3 src1_sel:DWORD
	ds_read_b128 v[66:69], v230
	ds_read_b128 v[70:73], v231
	ds_read_b128 v[74:77], v232
	ds_read_b128 v[78:81], v233
	ds_read_b128 v[182:185], v149
	ds_read_b128 v[186:189], v149 offset:2048
	ds_read_b128 v[190:193], v149 offset:4096
	ds_read_b128 v[194:197], v149 offset:6144
	v_add_u32_sdwa v234, v3, s25 dst_sel:DWORD dst_unused:UNUSED_PAD src0_sel:BYTE_0 src1_sel:DWORD
	v_add_u32_sdwa v235, v3, s25 dst_sel:DWORD dst_unused:UNUSED_PAD src0_sel:BYTE_1 src1_sel:DWORD
	v_add_u32_sdwa v236, v3, s25 dst_sel:DWORD dst_unused:UNUSED_PAD src0_sel:BYTE_2 src1_sel:DWORD
	v_add_u32_sdwa v237, v3, s25 dst_sel:DWORD dst_unused:UNUSED_PAD src0_sel:BYTE_3 src1_sel:DWORD
	s_waitcnt lgkmcnt(3)
	v_mfma_f32_32x32x16_bf16 v[66:81], v[182:185], v[110:113], v[66:81]
	ds_read_b128 v[82:85], v234
	ds_read_b128 v[86:89], v235
	ds_read_b128 v[90:93], v236
	ds_read_b128 v[94:97], v237
	ds_read_b128 v[198:201], v149 offset:512
	ds_read_b128 v[202:205], v149 offset:2560
	ds_read_b128 v[206:209], v149 offset:4608
	ds_read_b128 v[210:213], v149 offset:6656
	s_waitcnt lgkmcnt(10)
	v_mfma_f32_32x32x16_bf16 v[66:81], v[186:189], v[98:101], v[66:81]
	s_waitcnt lgkmcnt(9)
	v_mfma_f32_32x32x16_bf16 v[66:81], v[190:193], v[102:105], v[66:81]
	s_waitcnt lgkmcnt(8)
	v_mfma_f32_32x32x16_bf16 v[66:81], v[194:197], v[106:109], v[66:81]
	s_waitcnt lgkmcnt(3)
	v_mfma_f32_32x32x16_bf16 v[82:97], v[198:201], v[110:113], v[82:97]
	s_waitcnt lgkmcnt(2)
	v_mfma_f32_32x32x16_bf16 v[82:97], v[202:205], v[98:101], v[82:97]
	ds_read_b64_tr_b16 v[152:153], v150
	ds_read_b64_tr_b16 v[154:155], v150 offset:512
	ds_read_b64_tr_b16 v[156:157], v150 offset:1024
	ds_read_b64_tr_b16 v[158:159], v150 offset:1536
	ds_read_b64_tr_b16 v[160:161], v150 offset:2048
	ds_read_b64_tr_b16 v[162:163], v150 offset:2560
	ds_read_b64_tr_b16 v[164:165], v150 offset:3072
	ds_read_b64_tr_b16 v[166:167], v150 offset:3584
	v_exp_f32_e32 v66, v66
	v_exp_f32_e32 v67, v67
	v_exp_f32_e32 v68, v68
	v_exp_f32_e32 v69, v69
	s_waitcnt lgkmcnt(9)
	v_mfma_f32_32x32x16_bf16 v[82:97], v[206:209], v[102:105], v[82:97]
	v_exp_f32_e32 v70, v70
	v_exp_f32_e32 v71, v71
	v_exp_f32_e32 v72, v72
	v_exp_f32_e32 v73, v73
	s_waitcnt lgkmcnt(8)
	v_mfma_f32_32x32x16_bf16 v[82:97], v[210:213], v[106:109], v[82:97]
	v_exp_f32_e32 v74, v74
	v_exp_f32_e32 v75, v75
	v_exp_f32_e32 v76, v76
	v_exp_f32_e32 v77, v77
	v_exp_f32_e32 v78, v78
	v_exp_f32_e32 v79, v79
	v_exp_f32_e32 v80, v80
	v_exp_f32_e32 v81, v81
	ds_read_b64_tr_b16 v[168:169], v150 offset:4096
	ds_read_b64_tr_b16 v[170:171], v150 offset:4608
	ds_read_b64_tr_b16 v[172:173], v150 offset:5120
	ds_read_b64_tr_b16 v[174:175], v150 offset:5632
	ds_read_b64_tr_b16 v[214:215], v150 offset:6144
	ds_read_b64_tr_b16 v[216:217], v150 offset:6656
	ds_read_b64_tr_b16 v[218:219], v150 offset:7168
	ds_read_b64_tr_b16 v[220:221], v150 offset:7680
	v_cvt_pk_bf16_f32 v4, v66, v67
	v_cvt_pk_bf16_f32 v5, v68, v69
	v_cvt_pk_bf16_f32 v6, v70, v71
	v_cvt_pk_bf16_f32 v7, v72, v73
	v_cvt_pk_bf16_f32 v8, v74, v75
	v_cvt_pk_bf16_f32 v9, v76, v77
	v_cvt_pk_bf16_f32 v10, v78, v79
	v_cvt_pk_bf16_f32 v11, v80, v81
	s_waitcnt lgkmcnt(8)
	v_mfma_f32_32x32x16_bf16 v[34:49], v[4:7], v[152:155], v[34:49]
	v_exp_f32_e32 v82, v82
	v_exp_f32_e32 v83, v83
	v_exp_f32_e32 v84, v84
	s_waitcnt lgkmcnt(6)
	v_mfma_f32_32x32x16_bf16 v[18:33], v[4:7], v[168:171], v[18:33]
	v_exp_f32_e32 v85, v85
	v_exp_f32_e32 v86, v86
	v_exp_f32_e32 v87, v87
	v_mfma_f32_32x32x16_bf16 v[50:65], v[4:7], v[226:229], v[50:65]
	v_exp_f32_e32 v88, v88
	v_exp_f32_e32 v89, v89
	v_exp_f32_e32 v90, v90
	v_mfma_f32_32x32x16_bf16 v[34:49], v[8:11], v[156:159], v[34:49]
	v_exp_f32_e32 v91, v91
	v_exp_f32_e32 v92, v92
	v_exp_f32_e32 v93, v93
	s_waitcnt lgkmcnt(4)
	v_mfma_f32_32x32x16_bf16 v[18:33], v[8:11], v[172:175], v[18:33]
	v_exp_f32_e32 v94, v94
	v_exp_f32_e32 v95, v95
	v_exp_f32_e32 v96, v96
	v_exp_f32_e32 v97, v97
	v_mfma_f32_32x32x16_bf16 v[50:65], v[8:11], v[226:229], v[50:65]
	v_cvt_pk_bf16_f32 v12, v82, v83
	v_cvt_pk_bf16_f32 v13, v84, v85
	v_cvt_pk_bf16_f32 v14, v86, v87
	v_cvt_pk_bf16_f32 v15, v88, v89
	v_cvt_pk_bf16_f32 v222, v90, v91
	v_cvt_pk_bf16_f32 v223, v92, v93
	v_cvt_pk_bf16_f32 v224, v94, v95
	v_cvt_pk_bf16_f32 v225, v96, v97
	s_nop 1
	v_mfma_f32_32x32x16_bf16 v[34:49], v[12:15], v[160:163], v[34:49]
	s_waitcnt lgkmcnt(2)
	v_mfma_f32_32x32x16_bf16 v[18:33], v[12:15], v[214:217], v[18:33]
	v_mfma_f32_32x32x16_bf16 v[50:65], v[12:15], v[226:229], v[50:65]
	v_mfma_f32_32x32x16_bf16 v[34:49], v[222:225], v[164:167], v[34:49]
	s_waitcnt lgkmcnt(0)
	v_mfma_f32_32x32x16_bf16 v[18:33], v[222:225], v[218:221], v[18:33]
	v_mfma_f32_32x32x16_bf16 v[50:65], v[222:225], v[226:229], v[50:65]
	s_branch .LBB0_954

.LBB0_959:
	s_cmp_gt_i32 s83, 7
	s_cselect_b64 s[4:5], -1, 0
	s_and_b64 s[0:1], s[0:1], s[4:5]
	s_andn2_b64 vcc, exec, s[0:1]
	s_cbranch_vccnz .LBB0_1013
	s_waitcnt vmcnt(0)
	s_waitcnt vmcnt(0) lgkmcnt(0)
	s_barrier
	s_and_saveexec_b64 s[0:1], s[38:39]
	s_cbranch_execz .LBB0_1012
	s_add_u32 s98, s98, 1
	v_mov_b32_e32 v1, 0x25f20
	ds_read_b64 v[2:3], v1
	v_readlane_b32 s6, v238, 18
	v_readlane_b32 s7, v238, 19
	s_lshl_b32 s2, s87, 8
	s_addk_i32 s2, 0x1400
	v_mov_b32_e32 v1, s2
	v_mov_b32_e32 v5, 1
	s_nop 1
	global_atomic_add v1, v1, v5, s[6:7] sc0
	s_waitcnt vmcnt(0) lgkmcnt(0)
	v_readfirstlane_b32 s12, v1
	v_readfirstlane_b32 s9, v2
	v_readfirstlane_b32 s10, v3
	s_add_u32 s12, s12, 1
	s_mul_i32 s9, s9, s98
	s_mul_i32 s10, s10, s98
	v_mov_b32_e32 v1, 0x3400
	s_cmp_eq_u32 s12, s9
	s_cbranch_scc0 .Lfs2_spin
	buffer_wbl2 sc1
	s_waitcnt vmcnt(0)
	global_atomic_add v1, v5, s[6:7]

.LBB0_1147:
	s_barrier
	s_waitcnt vmcnt(0)
	v_readlane_b32 s38, v238, 36
	v_readlane_b32 s39, v238, 37
	s_barrier
	s_and_saveexec_b64 s[0:1], s[38:39]
	v_readlane_b32 s86, v238, 47
	v_readlane_b32 s87, v238, 46
	v_readlane_b32 s40, v238, 58
	v_readlane_b32 s93, v238, 48
	v_readlane_b32 s24, v238, 38
	v_readlane_b32 s41, v238, 59
	s_cbranch_execz .LBB0_1199
	s_add_u32 s98, s98, 1
	v_mov_b32_e32 v1, 0x25f20
	ds_read_b64 v[2:3], v1
	v_readlane_b32 s6, v238, 18
	v_readlane_b32 s7, v238, 19
	s_lshl_b32 s2, s87, 8
	s_addk_i32 s2, 0x1400
	v_mov_b32_e32 v1, s2
	v_mov_b32_e32 v5, 1
	s_nop 1
	global_atomic_add v1, v1, v5, s[6:7] sc0
	s_waitcnt vmcnt(0) lgkmcnt(0)
	v_readfirstlane_b32 s12, v1
	v_readfirstlane_b32 s9, v2
	v_readfirstlane_b32 s10, v3
	s_add_u32 s12, s12, 1
	s_mul_i32 s9, s9, s98
	s_mul_i32 s10, s10, s98
	v_mov_b32_e32 v1, 0x3400
	s_cmp_eq_u32 s12, s9
	s_cbranch_scc0 .Lfs3_spin
	buffer_wbl2 sc1
	s_waitcnt vmcnt(0)
	global_atomic_add v1, v5, s[6:7]

.LBB0_1221:
	s_cmp_gt_i32 s83, 8
	s_cselect_b64 s[0:1], -1, 0
	s_and_b64 s[4:5], s[4:5], s[0:1]
	s_andn2_b64 vcc, exec, s[4:5]
	s_mov_b64 s[60:61], s[38:39]
	s_cbranch_vccnz .LBB0_1275
	s_waitcnt vmcnt(0)
	s_waitcnt vmcnt(0) lgkmcnt(0)
	s_barrier
	s_and_saveexec_b64 s[4:5], s[38:39]
	s_cbranch_execz .LBB0_1274
	s_add_u32 s98, s98, 1
	v_mov_b32_e32 v1, 0x25f20
	ds_read_b64 v[2:3], v1
	v_readlane_b32 s6, v238, 18
	v_readlane_b32 s7, v238, 19
	s_lshl_b32 s2, s87, 8
	s_addk_i32 s2, 0x1400
	v_mov_b32_e32 v1, s2
	v_mov_b32_e32 v5, 1
	s_nop 1
	global_atomic_add v1, v1, v5, s[6:7] sc0
	s_waitcnt vmcnt(0) lgkmcnt(0)
	v_readfirstlane_b32 s12, v1
	v_readfirstlane_b32 s9, v2
	v_readfirstlane_b32 s10, v3
	s_add_u32 s12, s12, 1
	s_mul_i32 s9, s9, s98
	s_mul_i32 s10, s10, s98
	v_mov_b32_e32 v1, 0x3400
	s_cmp_eq_u32 s12, s9
	s_cbranch_scc0 .Lfs4_spin
	buffer_wbl2 sc1
	s_waitcnt vmcnt(0)
	global_atomic_add v1, v5, s[6:7]

.LBB0_1279:
	s_cmp_gt_i32 s83, 9
	s_cselect_b64 s[0:1], -1, 0
	s_and_b64 s[4:5], s[6:7], s[0:1]
	s_andn2_b64 vcc, exec, s[4:5]
	s_cbranch_vccnz .LBB0_1333
	s_waitcnt vmcnt(0)
	s_waitcnt vmcnt(0) lgkmcnt(0)
	s_barrier
	s_and_saveexec_b64 s[4:5], s[38:39]
	s_cbranch_execz .LBB0_1332
	s_add_u32 s98, s98, 1
	v_mov_b32_e32 v1, 0x25f20
	ds_read_b64 v[2:3], v1
	v_readlane_b32 s6, v238, 18
	v_readlane_b32 s7, v238, 19
	s_lshl_b32 s2, s87, 8
	s_addk_i32 s2, 0x1400
	v_mov_b32_e32 v1, s2
	v_mov_b32_e32 v5, 1
	s_nop 1
	global_atomic_add v1, v1, v5, s[6:7] sc0
	s_waitcnt vmcnt(0) lgkmcnt(0)
	v_readfirstlane_b32 s12, v1
	v_readfirstlane_b32 s9, v2
	v_readfirstlane_b32 s10, v3
	s_add_u32 s12, s12, 1
	s_mul_i32 s9, s9, s98
	s_mul_i32 s10, s10, s98
	v_mov_b32_e32 v1, 0x3400
	s_cmp_eq_u32 s12, s9
	s_cbranch_scc0 .Lfs5_spin
	buffer_wbl2 sc1
	s_waitcnt vmcnt(0)
	global_atomic_add v1, v5, s[6:7]

.LBB0_1360:
	s_cmp_lt_i32 s82, 11
	s_cselect_b64 s[4:5], -1, 0
	s_cmp_gt_i32 s83, 11
	s_cselect_b64 s[0:1], -1, 0
	s_and_b64 s[4:5], s[4:5], s[0:1]
	s_andn2_b64 vcc, exec, s[4:5]
	s_cbranch_vccnz .LBB0_1414
	s_waitcnt vmcnt(0)
	s_waitcnt vmcnt(0) lgkmcnt(0)
	s_barrier
	s_and_saveexec_b64 s[4:5], s[38:39]
	s_cbranch_execz .LBB0_1413
	s_add_u32 s98, s98, 1
	v_mov_b32_e32 v1, 0x25f20
	ds_read_b64 v[2:3], v1
	v_readlane_b32 s6, v238, 18
	v_readlane_b32 s7, v238, 19
	s_lshl_b32 s2, s87, 8
	s_addk_i32 s2, 0x1400
	v_mov_b32_e32 v1, s2
	v_mov_b32_e32 v5, 1
	s_nop 1
	global_atomic_add v1, v1, v5, s[6:7] sc0
	s_waitcnt vmcnt(0) lgkmcnt(0)
	v_readfirstlane_b32 s12, v1
	v_readfirstlane_b32 s9, v2
	v_readfirstlane_b32 s10, v3
	s_add_u32 s12, s12, 1
	s_mul_i32 s9, s9, s98
	s_mul_i32 s10, s10, s98
	v_mov_b32_e32 v1, 0x3400
	s_cmp_eq_u32 s12, s9
	s_cbranch_scc0 .Lfs6_spin
	buffer_wbl2 sc1
	s_waitcnt vmcnt(0)
	global_atomic_add v1, v5, s[6:7]

.LBB0_1457:
	s_cmp_gt_i32 s83, 12
	s_cselect_b64 s[0:1], -1, 0
	s_and_b64 s[4:5], s[6:7], s[0:1]
	s_andn2_b64 vcc, exec, s[4:5]
	s_cbranch_vccnz .LBB0_1511
	s_waitcnt vmcnt(0)
	s_waitcnt vmcnt(0) lgkmcnt(0)
	s_barrier
	s_and_saveexec_b64 s[4:5], s[38:39]
	s_cbranch_execz .LBB0_1510
	s_add_u32 s98, s98, 1
	v_mov_b32_e32 v1, 0x25f20
	ds_read_b64 v[2:3], v1
	v_readlane_b32 s6, v238, 18
	v_readlane_b32 s7, v238, 19
	s_lshl_b32 s2, s87, 8
	s_addk_i32 s2, 0x1400
	v_mov_b32_e32 v1, s2
	v_mov_b32_e32 v5, 1
	s_nop 1
	global_atomic_add v1, v1, v5, s[6:7] sc0
	s_waitcnt vmcnt(0) lgkmcnt(0)
	v_readfirstlane_b32 s12, v1
	v_readfirstlane_b32 s9, v2
	v_readfirstlane_b32 s10, v3
	s_add_u32 s12, s12, 1
	s_mul_i32 s9, s9, s98
	s_mul_i32 s10, s10, s98
	v_mov_b32_e32 v1, 0x3400
	s_cmp_eq_u32 s12, s9
	s_cbranch_scc0 .Lfs7_spin
	buffer_wbl2 sc1
	s_waitcnt vmcnt(0)
	global_atomic_add v1, v5, s[6:7]

.LBB0_1528:
	s_cmp_gt_i32 s83, 13
	s_cselect_b64 s[0:1], -1, 0
	s_and_b64 s[4:5], s[4:5], s[0:1]
	s_andn2_b64 vcc, exec, s[4:5]
	s_cbranch_vccnz .LBB0_1582
	s_waitcnt vmcnt(0)
	s_waitcnt vmcnt(0) lgkmcnt(0)
	s_barrier
	s_and_saveexec_b64 s[4:5], s[38:39]
	s_cbranch_execz .LBB0_1581
	s_add_u32 s98, s98, 1
	v_mov_b32_e32 v1, 0x25f20
	ds_read_b64 v[2:3], v1
	v_readlane_b32 s6, v238, 18
	v_readlane_b32 s7, v238, 19
	s_lshl_b32 s2, s87, 8
	s_addk_i32 s2, 0x1400
	v_mov_b32_e32 v1, s2
	v_mov_b32_e32 v5, 1
	s_nop 1
	global_atomic_add v1, v1, v5, s[6:7] sc0
	s_waitcnt vmcnt(0) lgkmcnt(0)
	v_readfirstlane_b32 s12, v1
	v_readfirstlane_b32 s9, v2
	v_readfirstlane_b32 s10, v3
	s_add_u32 s12, s12, 1
	s_mul_i32 s9, s9, s98
	s_mul_i32 s10, s10, s98
	v_mov_b32_e32 v1, 0x3400
	s_cmp_eq_u32 s12, s9
	s_cbranch_scc0 .Lfs8_spin
	buffer_wbl2 sc1
	s_waitcnt vmcnt(0)
	global_atomic_add v1, v5, s[6:7]

	.amdhsa_kernel _Z4mega4Args
		.amdhsa_group_segment_fixed_size 0
		.amdhsa_private_segment_fixed_size 0
		.amdhsa_kernarg_size 464
		.amdhsa_user_sgpr_count 2
		.amdhsa_user_sgpr_dispatch_ptr 0
		.amdhsa_user_sgpr_queue_ptr 0
		.amdhsa_user_sgpr_kernarg_segment_ptr 1
		.amdhsa_user_sgpr_dispatch_id 0
		.amdhsa_user_sgpr_kernarg_preload_length 0
		.amdhsa_user_sgpr_kernarg_preload_offset 0
		.amdhsa_user_sgpr_private_segment_size 0
		.amdhsa_uses_dynamic_stack 0
		.amdhsa_enable_private_segment 0
		.amdhsa_system_sgpr_workgroup_id_x 1
		.amdhsa_system_sgpr_workgroup_id_y 0
		.amdhsa_system_sgpr_workgroup_id_z 0
		.amdhsa_system_sgpr_workgroup_info 0
		.amdhsa_system_vgpr_workitem_id 0
		.amdhsa_next_free_vgpr 239
		.amdhsa_next_free_sgpr 102
		.amdhsa_accum_offset 240
		.amdhsa_reserve_vcc 1
		.amdhsa_float_round_mode_32 0
		.amdhsa_float_round_mode_16_64 0
		.amdhsa_float_denorm_mode_32 3
		.amdhsa_float_denorm_mode_16_64 3
		.amdhsa_dx10_clamp 1
		.amdhsa_ieee_mode 1
		.amdhsa_fp16_overflow 0
		.amdhsa_tg_split 0
		.amdhsa_exception_fp_ieee_invalid_op 0
		.amdhsa_exception_fp_denorm_src 0
		.amdhsa_exception_fp_ieee_div_zero 0
		.amdhsa_exception_fp_ieee_overflow 0
		.amdhsa_exception_fp_ieee_underflow 0
		.amdhsa_exception_fp_ieee_inexact 0
		.amdhsa_exception_int_div_zero 0
	.end_amdhsa_kernel

amdhsa.kernels:
  - .agpr_count:     0
    .args:
      - .offset:         0
        .size:           208
        .value_kind:     by_value
      - .offset:         208
        .size:           4
        .value_kind:     hidden_block_count_x
      - .offset:         212
        .size:           4
        .value_kind:     hidden_block_count_y
      - .offset:         216
        .size:           4
        .value_kind:     hidden_block_count_z
      - .offset:         220
        .size:           2
        .value_kind:     hidden_group_size_x
      - .offset:         222
        .size:           2
        .value_kind:     hidden_group_size_y
      - .offset:         224
        .size:           2
        .value_kind:     hidden_group_size_z
      - .offset:         226
        .size:           2
        .value_kind:     hidden_remainder_x
      - .offset:         228
        .size:           2
        .value_kind:     hidden_remainder_y
      - .offset:         230
        .size:           2
        .value_kind:     hidden_remainder_z
      - .offset:         248
        .size:           8
        .value_kind:     hidden_global_offset_x
      - .offset:         256
        .size:           8
        .value_kind:     hidden_global_offset_y
      - .offset:         264
        .size:           8
        .value_kind:     hidden_global_offset_z
      - .offset:         272
        .size:           2
        .value_kind:     hidden_grid_dims
      - .offset:         328
        .size:           4
        .value_kind:     hidden_dynamic_lds_size
    .group_segment_fixed_size: 0
    .kernarg_segment_align: 8
    .kernarg_segment_size: 464
    .language:       OpenCL C
    .language_version:
      - 2
      - 0
    .max_flat_workgroup_size: 512
    .name:           _Z4mega4Args
    .private_segment_fixed_size: 0
    .sgpr_count:     108
    .sgpr_spill_count: 62
    .symbol:         _Z4mega4Args.kd
    .uniform_work_group_size: 1
    .uses_dynamic_stack: false
    .vgpr_count:     239
    .vgpr_spill_count: 0
    .wavefront_size: 64
